# stack5 + write-through (sc1) bulk stores in the streaming elementwise phases (weight transposes, pre-norm, post-norm/residual phases) so the phase-end L2 write-back is empty
# speedup vs baseline: 1.0048x; 1.0048x over previous
; #define GAS __attribute__((address_space(1)))
; #define LAS __attribute__((address_space(3)))
; #define LDS_WAIT() asm volatile("s_waitcnt lgkmcnt(0)" ::: "memory")
; __device__ __forceinline__ unsigned pk2(float lo, float hi) { const f32x2_fr v = {lo, hi}; return __builtin_bit_cast(unsigned, __builtin_convertvector(v, bf16x2_fr)); }
; __device__ __forceinline__ void transpose_item(const float* W, int ldw, int Kdim, bf16* WT, int dst_row0, int k0, int n0, LAS float* scr, int lane, const float* gk) {
; #pragma unroll
;     for (int i = 0; i < 32; ++i) { const int kk = 2 * i + (lane >> 5); scr[kk * 33 + (lane & 31)] = W[(size_t)(k0 + kk) * ldw + n0 + (lane & 31)]; }
;     LDS_WAIT(); asm volatile("" ::: "memory");
;     const int c = lane & 7;
;     f32x4 ga = {1.f, 1.f, 1.f, 1.f}, gb = ga; if (gk) { ga = *(const f32x4*)(gk + k0 + 8 * c); gb = *(const f32x4*)(gk + k0 + 8 * c + 4); }
; #pragma unroll
;     for (int j = 0; j < 4; ++j) { const int n = (lane >> 3) + 8 * j; const LAS float* s = scr + (8 * c) * 33 + n;
;         v4u o; o.x = pk2(s[0 * 33] * ga.x, s[1 * 33] * ga.y); o.y = pk2(s[2 * 33] * ga.z, s[3 * 33] * ga.w); o.z = pk2(s[4 * 33] * gb.x, s[5 * 33] * gb.y); o.w = pk2(s[6 * 33] * gb.z, s[7 * 33] * gb.w);
;         *(GAS v4u*)(WT + (size_t)(dst_row0 + n) * Kdim + k0 + 8 * c) = o; }
;     LDS_WAIT(); asm volatile("" ::: "memory");
; }
.LBB0_10:
	ds_read2_b32 v[66:67], v48 offset1:8
	ds_read2_b32 v[68:69], v48 offset0:33 offset1:41
	ds_read2_b32 v[72:73], v48 offset0:66 offset1:74
	ds_read2_b32 v[74:75], v48 offset0:99 offset1:107
	ds_read2_b32 v[76:77], v48 offset0:132 offset1:140
	ds_read2_b32 v[78:79], v48 offset0:165 offset1:173
	ds_read2_b32 v[80:81], v48 offset0:198 offset1:206
	ds_read2_b32 v[82:83], v48 offset0:231 offset1:239
	s_waitcnt lgkmcnt(7)
	v_mov_b32_e32 v62, v66
	s_waitcnt lgkmcnt(6)
	v_mov_b32_e32 v63, v68
	s_waitcnt lgkmcnt(5)
	v_mov_b32_e32 v64, v72
	s_waitcnt lgkmcnt(4)
	v_mov_b32_e32 v65, v74
	s_mul_hi_i32 s18, s34, 0x600000
	s_mul_i32 s34, s34, 0x600000
	s_waitcnt vmcnt(0)
	v_pk_mul_f32 v[62:63], v[6:7], v[62:63]
	v_pk_mul_f32 v[64:65], v[8:9], v[64:65]
	s_add_u32 s37, s2, s34
	v_cvt_pk_bf16_f32 v62, v62, v63
	v_cvt_pk_bf16_f32 v63, v64, v65
	s_waitcnt lgkmcnt(3)
	v_mov_b32_e32 v64, v76
	s_waitcnt lgkmcnt(2)
	v_mov_b32_e32 v65, v78
	s_waitcnt lgkmcnt(1)
	v_mov_b32_e32 v84, v80
	s_waitcnt lgkmcnt(0)
	v_mov_b32_e32 v85, v82
	s_addc_u32 s18, s3, s18
	s_lshl_b64 s[34:35], s[38:39], 1
	v_pk_mul_f32 v[64:65], v[2:3], v[64:65]
	v_pk_mul_f32 v[84:85], v[4:5], v[84:85]
	s_add_u32 s34, s37, s34
	v_cvt_pk_bf16_f32 v64, v64, v65
	v_cvt_pk_bf16_f32 v65, v84, v85
	v_or_b32_e32 v84, s36, v47
	s_addc_u32 s35, s18, s35
	v_mov_b32_e32 v15, v11
	v_ashrrev_i32_e32 v85, 31, v84
	v_lshl_add_u64 v[70:71], s[34:35], 0, v[14:15]
	v_lshlrev_b64 v[84:85], 11, v[84:85]
	v_lshl_add_u64 v[84:85], v[70:71], 0, v[84:85]
	v_mov_b32_e32 v68, v67
	v_mov_b32_e32 v74, v73
	global_store_dwordx4 v[84:85], v[62:65], off sc1
	v_mov_b32_e32 v78, v77
	v_mov_b32_e32 v82, v81
	v_pk_mul_f32 v[62:63], v[6:7], v[68:69]
	v_pk_mul_f32 v[64:65], v[8:9], v[74:75]
	v_cvt_pk_bf16_f32 v62, v62, v63
	v_cvt_pk_bf16_f32 v63, v64, v65
	v_pk_mul_f32 v[64:65], v[2:3], v[78:79]
	v_pk_mul_f32 v[66:67], v[4:5], v[82:83]
	v_cvt_pk_bf16_f32 v64, v64, v65
	v_cvt_pk_bf16_f32 v65, v66, v67
	v_or_b32_e32 v66, s36, v49
	v_ashrrev_i32_e32 v67, 31, v66
	v_lshlrev_b64 v[66:67], 11, v[66:67]
	v_lshl_add_u64 v[66:67], v[70:71], 0, v[66:67]
	ds_read2_b32 v[68:69], v48 offset0:16 offset1:24
	ds_read2_b32 v[72:73], v48 offset0:49 offset1:57
	global_store_dwordx4 v[66:67], v[62:65], off sc1
	ds_read2_b32 v[66:67], v48 offset0:82 offset1:90
	ds_read2_b32 v[74:75], v48 offset0:115 offset1:123
	ds_read2_b32 v[76:77], v48 offset0:148 offset1:156
	ds_read2_b32 v[78:79], v48 offset0:181 offset1:189
	ds_read2_b32 v[80:81], v48 offset0:214 offset1:222
	ds_read2_b32 v[82:83], v48 offset0:247 offset1:255
	s_waitcnt lgkmcnt(7)
	v_mov_b32_e32 v62, v68
	s_waitcnt lgkmcnt(6)
	v_mov_b32_e32 v63, v72
	s_waitcnt lgkmcnt(5)
	v_mov_b32_e32 v64, v66
	s_waitcnt lgkmcnt(4)
	v_mov_b32_e32 v65, v74
	v_pk_mul_f32 v[62:63], v[6:7], v[62:63]
	v_pk_mul_f32 v[64:65], v[8:9], v[64:65]
	v_cvt_pk_bf16_f32 v62, v62, v63
	v_cvt_pk_bf16_f32 v63, v64, v65
	s_waitcnt lgkmcnt(3)
	v_mov_b32_e32 v64, v76
	s_waitcnt lgkmcnt(2)
	v_mov_b32_e32 v65, v78
	v_mov_b32_e32 v72, v69
	v_mov_b32_e32 v74, v67
	v_mov_b32_e32 v78, v77
	v_pk_mul_f32 v[64:65], v[2:3], v[64:65]
	s_waitcnt lgkmcnt(1)
	v_mov_b32_e32 v84, v80
	s_waitcnt lgkmcnt(0)
	v_mov_b32_e32 v85, v82
	v_pk_mul_f32 v[6:7], v[6:7], v[72:73]
	v_pk_mul_f32 v[8:9], v[8:9], v[74:75]
	v_pk_mul_f32 v[2:3], v[2:3], v[78:79]
	v_mov_b32_e32 v82, v81
	v_pk_mul_f32 v[84:85], v[4:5], v[84:85]
	v_cvt_pk_bf16_f32 v6, v6, v7
	v_cvt_pk_bf16_f32 v7, v8, v9
	v_cvt_pk_bf16_f32 v8, v2, v3
	v_pk_mul_f32 v[2:3], v[4:5], v[82:83]
	v_cvt_pk_bf16_f32 v64, v64, v65
	v_cvt_pk_bf16_f32 v65, v84, v85
	v_or_b32_e32 v84, s36, v50
	v_cvt_pk_bf16_f32 v9, v2, v3
	v_or_b32_e32 v2, s36, v51
	v_ashrrev_i32_e32 v85, 31, v84
	v_ashrrev_i32_e32 v3, 31, v2
	v_lshlrev_b64 v[84:85], 11, v[84:85]
	v_lshlrev_b64 v[2:3], 11, v[2:3]
	v_lshl_add_u64 v[84:85], v[70:71], 0, v[84:85]
	v_lshl_add_u64 v[2:3], v[70:71], 0, v[2:3]
	global_store_dwordx4 v[84:85], v[62:65], off sc1
	global_store_dwordx4 v[2:3], v[6:9], off sc1
	s_waitcnt lgkmcnt(0)

; #define LAS __attribute__((address_space(3)))
; __device__ __forceinline__ void transpose_item(const float* W, int ldw, int Kdim, bf16* WT, int dst_row0, int k0, int n0, LAS float* scr, int lane, const float* gk) {
; #pragma unroll
;     for (int i = 0; i < 32; ++i) { const int kk = 2 * i + (lane >> 5); scr[kk * 33 + (lane & 31)] = W[(size_t)(k0 + kk) * ldw + n0 + (lane & 31)]; }
; __global__ void __launch_bounds__(NWAVES * 64, 2) hymba_fwd(Args args_unused) {
;     ...
;         for (int it = gw; it < DEPTH * I_L; it += NGW) {
;             const int l = it / I_L; int r = it % I_L;
;             if (r < I_IN) { const int nb = NQKV / 32; transpose_item(w_in + (size_t)l * D * INW, INW, D, WIN_T + (size_t)l * NQKV * D, 32 * (r % nb), 64 * (r / nb), 32 * (r % nb), scr, lane, attn_pre_g + l * D); continue; } r -= I_IN;
;             if (r < I_O) { const int nb = D / 32; transpose_item(w_out + (size_t)l * D * D, D, D, WO_T + (size_t)l * D * D, 32 * (r % nb), 64 * (r / nb), 32 * (r % nb), scr, lane, nullptr); continue; } r -= I_O;
;             if (r < 2 * I_G) { const int up = r >= I_G; if (up) r -= I_G; const int nb = DFF / 32, n0 = 32 * (r % nb);
;                 transpose_item((up ? w_up : w_gate) + (size_t)l * D * DFF, DFF, D, WGU_T + (size_t)l * NGU * D, (n0 / 128) * 256 + up * 128 + (n0 % 128), 64 * (r / nb), n0, scr, lane, ffn_pre_g + l * D); continue; } r -= 2 * I_G;
;             { const int nb = D / 32; transpose_item(w_down + (size_t)l * DFF * D, D, DFF, WD_T + (size_t)l * D * DFF, 32 * (r % nb), 64 * (r / nb), 32 * (r % nb), scr, lane, nullptr); }
.LBB0_12:
	s_mul_hi_i32 s18, s1, 0x5397829d
	s_lshr_b32 s34, s18, 31
	s_ashr_i32 s18, s18, 11
	s_add_i32 s34, s18, s34
	s_mul_i32 s38, s34, 0xffffe780
	s_add_i32 s50, s1, s38
	s_cmpk_gt_i32 s50, 0x5ff
	s_mov_b64 s[36:37], -1
	s_cbranch_scc0 .LBB0_25
	s_cmpk_gt_u32 s50, 0x7ff
	s_cbranch_scc0 .LBB0_22
	s_cmpk_gt_u32 s50, 0x12ff
	s_mul_hi_i32 s35, s34, 0xb00000
	s_mul_i32 s51, s34, 0xb00000
	s_cbranch_scc0 .LBB0_16
	s_add_u32 s40, s10, s51
	s_addc_u32 s41, s11, s35
	s_mul_i32 s36, s34, 0x580000
	s_mul_hi_i32 s18, s34, 0x580000
	s_add_u32 s37, s42, s36
	s_addc_u32 s39, s43, s18
	s_mul_i32 s18, s34, 0xffffcf00
	s_add_i32 s18, s44, s18
	s_and_b32 s36, s46, 0x3e0
	s_and_b32 s18, s18, 0x7fffffc0
	s_addk_i32 s18, 0xda00
	s_lshl_b32 s52, s36, 2
	s_add_u32 s40, s40, s52
	s_addc_u32 s41, s41, 0
	v_or_b32_e32 v4, s18, v13
	v_mov_b32_e32 v5, v11
	v_or_b32_e32 v6, s18, v16
	v_mov_b32_e32 v7, v11
	v_or_b32_e32 v8, s18, v17
	v_mov_b32_e32 v9, v11
	v_or_b32_e32 v62, s18, v18
	v_mov_b32_e32 v63, v11
	v_or_b32_e32 v64, s18, v19
	v_mov_b32_e32 v65, v11
	v_or_b32_e32 v66, s18, v20
	v_mov_b32_e32 v67, v11
	v_or_b32_e32 v68, s18, v21
	v_mov_b32_e32 v69, v11
	v_or_b32_e32 v70, s18, v22
	v_mov_b32_e32 v71, v11
	v_lshl_add_u64 v[2:3], s[40:41], 0, v[10:11]
	v_lshlrev_b64 v[4:5], 12, v[4:5]
	v_lshlrev_b64 v[6:7], 12, v[6:7]
	v_lshlrev_b64 v[8:9], 12, v[8:9]
	v_lshlrev_b64 v[62:63], 12, v[62:63]
	v_lshlrev_b64 v[64:65], 12, v[64:65]
	v_lshlrev_b64 v[66:67], 12, v[66:67]
	v_lshlrev_b64 v[68:69], 12, v[68:69]
	v_lshlrev_b64 v[70:71], 12, v[70:71]
	v_lshl_add_u64 v[4:5], v[2:3], 0, v[4:5]
	v_lshl_add_u64 v[6:7], v[2:3], 0, v[6:7]
	v_lshl_add_u64 v[8:9], v[2:3], 0, v[8:9]
	v_lshl_add_u64 v[62:63], v[2:3], 0, v[62:63]
	v_lshl_add_u64 v[64:65], v[2:3], 0, v[64:65]
	v_lshl_add_u64 v[66:67], v[2:3], 0, v[66:67]
	v_lshl_add_u64 v[68:69], v[2:3], 0, v[68:69]
	v_lshl_add_u64 v[70:71], v[2:3], 0, v[70:71]
	global_load_dword v15, v[4:5], off
	global_load_dword v72, v[6:7], off
	global_load_dword v73, v[8:9], off
	global_load_dword v74, v[62:63], off
	global_load_dword v75, v[64:65], off
	global_load_dword v76, v[66:67], off
	global_load_dword v77, v[68:69], off
	global_load_dword v78, v[70:71], off
	v_or_b32_e32 v4, s18, v23
	v_mov_b32_e32 v5, v11
	v_or_b32_e32 v6, s18, v24
	v_mov_b32_e32 v7, v11
	v_or_b32_e32 v8, s18, v25
	v_mov_b32_e32 v9, v11
	v_or_b32_e32 v62, s18, v26
	v_mov_b32_e32 v63, v11
	v_or_b32_e32 v64, s18, v27
	v_mov_b32_e32 v65, v11
	v_or_b32_e32 v66, s18, v28
	v_mov_b32_e32 v67, v11
	v_or_b32_e32 v68, s18, v29
	v_mov_b32_e32 v69, v11
	v_or_b32_e32 v70, s18, v30
	v_mov_b32_e32 v71, v11
	v_lshlrev_b64 v[4:5], 12, v[4:5]
	v_lshlrev_b64 v[6:7], 12, v[6:7]
	v_lshlrev_b64 v[8:9], 12, v[8:9]
	v_lshlrev_b64 v[62:63], 12, v[62:63]
	v_lshlrev_b64 v[64:65], 12, v[64:65]
	v_lshlrev_b64 v[66:67], 12, v[66:67]
	v_lshlrev_b64 v[68:69], 12, v[68:69]
	v_lshlrev_b64 v[70:71], 12, v[70:71]
	v_lshl_add_u64 v[4:5], v[2:3], 0, v[4:5]
	v_lshl_add_u64 v[6:7], v[2:3], 0, v[6:7]
	v_lshl_add_u64 v[8:9], v[2:3], 0, v[8:9]
	v_lshl_add_u64 v[62:63], v[2:3], 0, v[62:63]
	v_lshl_add_u64 v[64:65], v[2:3], 0, v[64:65]
	v_lshl_add_u64 v[66:67], v[2:3], 0, v[66:67]
	v_lshl_add_u64 v[68:69], v[2:3], 0, v[68:69]
	v_lshl_add_u64 v[70:71], v[2:3], 0, v[70:71]
	global_load_dword v79, v[4:5], off
	global_load_dword v80, v[6:7], off
	global_load_dword v81, v[8:9], off
	global_load_dword v82, v[62:63], off
	global_load_dword v83, v[64:65], off
	global_load_dword v84, v[66:67], off
	global_load_dword v85, v[68:69], off
	global_load_dword v86, v[70:71], off
	v_or_b32_e32 v4, s18, v31
	v_mov_b32_e32 v5, v11
	v_or_b32_e32 v6, s18, v32
	v_mov_b32_e32 v7, v11
	v_or_b32_e32 v8, s18, v33
	v_mov_b32_e32 v9, v11
	v_or_b32_e32 v62, s18, v34
	v_mov_b32_e32 v63, v11
	v_or_b32_e32 v64, s18, v35
	v_mov_b32_e32 v65, v11
	v_or_b32_e32 v66, s18, v36
	v_mov_b32_e32 v67, v11
	v_or_b32_e32 v68, s18, v37
	v_mov_b32_e32 v69, v11
	v_or_b32_e32 v70, s18, v38
	v_mov_b32_e32 v71, v11
	v_lshlrev_b64 v[4:5], 12, v[4:5]
	v_lshlrev_b64 v[6:7], 12, v[6:7]
	v_lshlrev_b64 v[8:9], 12, v[8:9]
	v_lshlrev_b64 v[62:63], 12, v[62:63]
	v_lshlrev_b64 v[64:65], 12, v[64:65]
	v_lshlrev_b64 v[66:67], 12, v[66:67]
	v_lshlrev_b64 v[68:69], 12, v[68:69]
	v_lshlrev_b64 v[70:71], 12, v[70:71]
	v_lshl_add_u64 v[4:5], v[2:3], 0, v[4:5]
	v_lshl_add_u64 v[6:7], v[2:3], 0, v[6:7]
	v_lshl_add_u64 v[8:9], v[2:3], 0, v[8:9]
	v_lshl_add_u64 v[62:63], v[2:3], 0, v[62:63]
	v_lshl_add_u64 v[64:65], v[2:3], 0, v[64:65]
	v_lshl_add_u64 v[66:67], v[2:3], 0, v[66:67]
	v_lshl_add_u64 v[68:69], v[2:3], 0, v[68:69]
	v_lshl_add_u64 v[70:71], v[2:3], 0, v[70:71]
	global_load_dword v87, v[4:5], off
	global_load_dword v88, v[6:7], off
	global_load_dword v89, v[8:9], off
	global_load_dword v90, v[62:63], off
	global_load_dword v91, v[64:65], off
	global_load_dword v92, v[66:67], off
	global_load_dword v93, v[68:69], off
	global_load_dword v94, v[70:71], off
	v_or_b32_e32 v4, s18, v39
	v_mov_b32_e32 v5, v11
	v_or_b32_e32 v6, s18, v40
	v_mov_b32_e32 v7, v11
	v_or_b32_e32 v8, s18, v41
	v_mov_b32_e32 v9, v11
	v_or_b32_e32 v62, s18, v42
	v_mov_b32_e32 v63, v11
	v_or_b32_e32 v64, s18, v43
	v_mov_b32_e32 v65, v11
	v_or_b32_e32 v66, s18, v44
	v_mov_b32_e32 v67, v11
	v_or_b32_e32 v68, s18, v45
	v_mov_b32_e32 v69, v11
	v_or_b32_e32 v70, s18, v46
	v_mov_b32_e32 v71, v11
	v_lshlrev_b64 v[4:5], 12, v[4:5]
	v_lshlrev_b64 v[6:7], 12, v[6:7]
	v_lshlrev_b64 v[8:9], 12, v[8:9]
	v_lshlrev_b64 v[62:63], 12, v[62:63]
	v_lshlrev_b64 v[64:65], 12, v[64:65]
	v_lshlrev_b64 v[66:67], 12, v[66:67]
	v_lshlrev_b64 v[68:69], 12, v[68:69]
	v_lshlrev_b64 v[70:71], 12, v[70:71]
	v_lshl_add_u64 v[4:5], v[2:3], 0, v[4:5]
	v_lshl_add_u64 v[6:7], v[2:3], 0, v[6:7]
	v_lshl_add_u64 v[8:9], v[2:3], 0, v[8:9]
	v_lshl_add_u64 v[62:63], v[2:3], 0, v[62:63]
	v_lshl_add_u64 v[64:65], v[2:3], 0, v[64:65]
	v_lshl_add_u64 v[66:67], v[2:3], 0, v[66:67]
	v_lshl_add_u64 v[68:69], v[2:3], 0, v[68:69]
	v_lshl_add_u64 v[2:3], v[2:3], 0, v[70:71]
	global_load_dword v4, v[4:5], off
	s_nop 0
	global_load_dword v5, v[6:7], off
	s_nop 0
	global_load_dword v6, v[8:9], off
	global_load_dword v7, v[62:63], off
	s_nop 0
	global_load_dword v8, v[64:65], off
	global_load_dword v9, v[66:67], off
	global_load_dword v62, v[68:69], off
	s_nop 0
	global_load_dword v2, v[2:3], off
	s_waitcnt vmcnt(30)
; #define GAS __attribute__((address_space(1)))
; #define LAS __attribute__((address_space(3)))
; #define LDS_WAIT() asm volatile("s_waitcnt lgkmcnt(0)" ::: "memory")
; __device__ __forceinline__ unsigned pk2(float lo, float hi) { const f32x2_fr v = {lo, hi}; return __builtin_bit_cast(unsigned, __builtin_convertvector(v, bf16x2_fr)); }
; __device__ __forceinline__ void transpose_item(const float* W, int ldw, int Kdim, bf16* WT, int dst_row0, int k0, int n0, LAS float* scr, int lane, const float* gk) {
;     ...
;     for (int i = 0; i < 32; ++i) { const int kk = 2 * i + (lane >> 5); scr[kk * 33 + (lane & 31)] = W[(size_t)(k0 + kk) * ldw + n0 + (lane & 31)]; }
;     LDS_WAIT(); asm volatile("" ::: "memory");
;     const int c = lane & 7;
;     f32x4 ga = {1.f, 1.f, 1.f, 1.f}, gb = ga; if (gk) { ga = *(const f32x4*)(gk + k0 + 8 * c); gb = *(const f32x4*)(gk + k0 + 8 * c + 4); }
; #pragma unroll
;     for (int j = 0; j < 4; ++j) { const int n = (lane >> 3) + 8 * j; const LAS float* s = scr + (8 * c) * 33 + n;
;         v4u o; o.x = pk2(s[0 * 33] * ga.x, s[1 * 33] * ga.y); o.y = pk2(s[2 * 33] * ga.z, s[3 * 33] * ga.w); o.z = pk2(s[4 * 33] * gb.x, s[5 * 33] * gb.y); o.w = pk2(s[6 * 33] * gb.z, s[7 * 33] * gb.w);
;         *(GAS v4u*)(WT + (size_t)(dst_row0 + n) * Kdim + k0 + 8 * c) = o; }
;     LDS_WAIT(); asm volatile("" ::: "memory");
	ds_write2_b32 v52, v15, v72 offset1:66
	s_waitcnt vmcnt(28)
	ds_write2_b32 v52, v73, v74 offset0:132 offset1:198
	s_waitcnt vmcnt(26)
	ds_write2_b32 v56, v75, v76 offset0:8 offset1:74
	s_waitcnt vmcnt(24)
	ds_write2_b32 v53, v77, v78 offset1:66
	s_waitcnt vmcnt(22)
	ds_write2_b32 v53, v79, v80 offset0:132 offset1:198
	s_waitcnt vmcnt(20)
	ds_write2_b32 v57, v81, v82 offset0:8 offset1:74
	s_waitcnt vmcnt(18)
	ds_write2_b32 v54, v83, v84 offset1:66
	s_waitcnt vmcnt(16)
	ds_write2_b32 v54, v85, v86 offset0:132 offset1:198
	s_waitcnt vmcnt(14)
	ds_write2_b32 v58, v87, v88 offset0:8 offset1:74
	s_waitcnt vmcnt(12)
	ds_write2_b32 v55, v89, v90 offset1:66
	s_waitcnt vmcnt(10)
	ds_write2_b32 v55, v91, v92 offset0:132 offset1:198
	s_waitcnt vmcnt(8)
	ds_write2_b32 v59, v93, v94 offset0:8 offset1:74
	s_waitcnt vmcnt(6)
	ds_write2_b32 v59, v4, v5 offset0:140 offset1:206
	s_waitcnt vmcnt(4)
	ds_write2_b32 v60, v6, v7 offset0:16 offset1:82
	s_waitcnt vmcnt(2)
	ds_write2_b32 v60, v8, v9 offset0:148 offset1:214
	s_waitcnt vmcnt(0)
	ds_write2_b32 v61, v62, v2 offset0:24 offset1:90
	s_waitcnt lgkmcnt(0)
	ds_read2_b32 v[6:7], v48 offset0:33 offset1:41
	ds_read2_b32 v[8:9], v48 offset1:8
	ds_read2_b32 v[62:63], v48 offset0:66 offset1:74
	ds_read2_b32 v[64:65], v48 offset0:99 offset1:107
	ds_read2_b32 v[66:67], v48 offset0:132 offset1:140
	ds_read2_b32 v[68:69], v48 offset0:165 offset1:173
	ds_read2_b32 v[70:71], v48 offset0:198 offset1:206
	ds_read2_b32 v[72:73], v48 offset0:231 offset1:239
	s_lshl_b64 s[40:41], s[18:19], 1
	s_add_u32 s40, s37, s40
	s_waitcnt lgkmcnt(6)
	v_cvt_pk_bf16_f32 v2, v8, v6
	v_or_b32_e32 v6, s36, v47
	s_addc_u32 s41, s39, s41
	v_mov_b32_e32 v15, v11
	v_mul_u32_u24_e32 v6, 0xb00, v6
	v_lshl_add_u64 v[74:75], s[40:41], 0, v[14:15]
	v_lshlrev_b32_e32 v76, 1, v6
	v_mov_b32_e32 v77, v11
	s_waitcnt lgkmcnt(4)
	v_cvt_pk_bf16_f32 v3, v62, v64
	s_waitcnt lgkmcnt(2)
	v_cvt_pk_bf16_f32 v4, v66, v68
	s_waitcnt lgkmcnt(0)
	v_cvt_pk_bf16_f32 v5, v70, v72
	v_lshl_add_u64 v[76:77], v[74:75], 0, v[76:77]
	v_or_b32_e32 v6, s36, v49
	global_store_dwordx4 v[76:77], v[2:5], off sc1
	v_mul_u32_u24_e32 v6, 0xb00, v6
	v_lshlrev_b32_e32 v6, 1, v6
	v_cvt_pk_bf16_f32 v2, v9, v7
	v_cvt_pk_bf16_f32 v3, v63, v65
	v_cvt_pk_bf16_f32 v4, v67, v69
	v_cvt_pk_bf16_f32 v5, v71, v73
	v_mov_b32_e32 v7, v11
	ds_read2_b32 v[8:9], v48 offset0:16 offset1:24
	ds_read2_b32 v[62:63], v48 offset0:49 offset1:57
	ds_read2_b32 v[64:65], v48 offset0:82 offset1:90
	ds_read2_b32 v[66:67], v48 offset0:115 offset1:123
	ds_read2_b32 v[68:69], v48 offset0:148 offset1:156
	ds_read2_b32 v[70:71], v48 offset0:181 offset1:189
	ds_read2_b32 v[72:73], v48 offset0:214 offset1:222
	ds_read2_b32 v[76:77], v48 offset0:247 offset1:255
	v_lshl_add_u64 v[6:7], v[74:75], 0, v[6:7]
	global_store_dwordx4 v[6:7], v[2:5], off sc1
	v_or_b32_e32 v6, s36, v50
	v_mul_u32_u24_e32 v6, 0xb00, v6
	v_lshlrev_b32_e32 v6, 1, v6
	v_mov_b32_e32 v7, v11
	s_waitcnt lgkmcnt(6)
	v_cvt_pk_bf16_f32 v2, v8, v62
	s_waitcnt lgkmcnt(4)
	v_cvt_pk_bf16_f32 v3, v64, v66
	s_waitcnt lgkmcnt(2)
	v_cvt_pk_bf16_f32 v4, v68, v70
	s_waitcnt lgkmcnt(0)
	v_cvt_pk_bf16_f32 v5, v72, v76
	v_lshl_add_u64 v[6:7], v[74:75], 0, v[6:7]
	global_store_dwordx4 v[6:7], v[2:5], off sc1
	v_or_b32_e32 v6, s36, v51
	v_mul_u32_u24_e32 v6, 0xb00, v6
	v_lshlrev_b32_e32 v6, 1, v6
	v_mov_b32_e32 v7, v11
	v_cvt_pk_bf16_f32 v2, v9, v63
	v_cvt_pk_bf16_f32 v3, v65, v67
	v_cvt_pk_bf16_f32 v4, v69, v71
	v_cvt_pk_bf16_f32 v5, v73, v77
	v_lshl_add_u64 v[6:7], v[74:75], 0, v[6:7]
	global_store_dwordx4 v[6:7], v[2:5], off sc1
	s_waitcnt lgkmcnt(0)
	s_mov_b64 s[36:37], 0

; #define GAS __attribute__((address_space(1)))
; #define LAS __attribute__((address_space(3)))
; #define LDS_WAIT() asm volatile("s_waitcnt lgkmcnt(0)" ::: "memory")
; __device__ __forceinline__ unsigned pk2(float lo, float hi) { const f32x2_fr v = {lo, hi}; return __builtin_bit_cast(unsigned, __builtin_convertvector(v, bf16x2_fr)); }
; __device__ __forceinline__ void transpose_item(const float* W, int ldw, int Kdim, bf16* WT, int dst_row0, int k0, int n0, LAS float* scr, int lane, const float* gk) {
;     ...
;     const int c = lane & 7;
;     f32x4 ga = {1.f, 1.f, 1.f, 1.f}, gb = ga; if (gk) { ga = *(const f32x4*)(gk + k0 + 8 * c); gb = *(const f32x4*)(gk + k0 + 8 * c + 4); }
; #pragma unroll
;     for (int j = 0; j < 4; ++j) { const int n = (lane >> 3) + 8 * j; const LAS float* s = scr + (8 * c) * 33 + n;
;         v4u o; o.x = pk2(s[0 * 33] * ga.x, s[1 * 33] * ga.y); o.y = pk2(s[2 * 33] * ga.z, s[3 * 33] * ga.w); o.z = pk2(s[4 * 33] * gb.x, s[5 * 33] * gb.y); o.w = pk2(s[6 * 33] * gb.z, s[7 * 33] * gb.w);
;         *(GAS v4u*)(WT + (size_t)(dst_row0 + n) * Kdim + k0 + 8 * c) = o; }
;     LDS_WAIT(); asm volatile("" ::: "memory");
.LBB0_20:
	s_and_b64 s[36:37], s[36:37], exec
	ds_read2_b32 v[66:67], v48 offset1:8
	ds_read2_b32 v[68:69], v48 offset0:33 offset1:41
	ds_read2_b32 v[72:73], v48 offset0:66 offset1:74
	ds_read2_b32 v[74:75], v48 offset0:99 offset1:107
	s_cselect_b32 s36, 0x80, 0
	s_add_u32 s39, s29, s51
	s_addc_u32 s35, s33, s35
	s_lshl_b32 s37, s52, 6
	ds_read2_b32 v[76:77], v48 offset0:132 offset1:140
	ds_read2_b32 v[78:79], v48 offset0:165 offset1:173
	ds_read2_b32 v[80:81], v48 offset0:198 offset1:206
	ds_read2_b32 v[82:83], v48 offset0:231 offset1:239
	s_and_b32 s37, s37, 0x1f00
	s_or_b32 s36, s37, s36
	s_and_b32 s37, s38, 0x60
	s_or_b32 s38, s36, s37
	s_lshl_b64 s[36:37], s[18:19], 1
	s_waitcnt lgkmcnt(7)
	v_mov_b32_e32 v62, v66
	s_waitcnt lgkmcnt(6)
	v_mov_b32_e32 v63, v68
	s_waitcnt lgkmcnt(5)
	v_mov_b32_e32 v64, v72
	s_waitcnt lgkmcnt(4)
	v_mov_b32_e32 v65, v74
	s_add_u32 s36, s39, s36
	s_waitcnt vmcnt(0)
	v_pk_mul_f32 v[62:63], v[6:7], v[62:63]
	v_pk_mul_f32 v[64:65], v[8:9], v[64:65]
	s_addc_u32 s37, s35, s37
	v_mov_b32_e32 v15, v11
	v_cvt_pk_bf16_f32 v62, v62, v63
	v_cvt_pk_bf16_f32 v63, v64, v65
	s_waitcnt lgkmcnt(3)
	v_mov_b32_e32 v64, v76
	s_waitcnt lgkmcnt(2)
	v_mov_b32_e32 v65, v78
	s_waitcnt lgkmcnt(1)
	v_mov_b32_e32 v84, v80
	s_waitcnt lgkmcnt(0)
	v_mov_b32_e32 v85, v82
	v_lshl_add_u64 v[70:71], s[36:37], 0, v[14:15]
	v_pk_mul_f32 v[64:65], v[2:3], v[64:65]
	v_pk_mul_f32 v[84:85], v[4:5], v[84:85]
	v_or_b32_e32 v15, s38, v47
	v_cvt_pk_bf16_f32 v64, v64, v65
	v_cvt_pk_bf16_f32 v65, v84, v85
	v_lshlrev_b32_e32 v84, 11, v15
	v_mov_b32_e32 v85, v11
	v_lshl_add_u64 v[84:85], v[70:71], 0, v[84:85]
	v_mov_b32_e32 v68, v67
	v_mov_b32_e32 v74, v73
	global_store_dwordx4 v[84:85], v[62:65], off sc1
	v_mov_b32_e32 v78, v77
	v_mov_b32_e32 v82, v81
	v_pk_mul_f32 v[62:63], v[6:7], v[68:69]
	v_pk_mul_f32 v[64:65], v[8:9], v[74:75]
	v_cvt_pk_bf16_f32 v62, v62, v63
	v_cvt_pk_bf16_f32 v63, v64, v65
	v_pk_mul_f32 v[64:65], v[2:3], v[78:79]
	v_pk_mul_f32 v[66:67], v[4:5], v[82:83]
	v_or_b32_e32 v15, s38, v49
	v_cvt_pk_bf16_f32 v64, v64, v65
	v_cvt_pk_bf16_f32 v65, v66, v67
	v_lshlrev_b32_e32 v66, 11, v15
	v_mov_b32_e32 v67, v11
	v_lshl_add_u64 v[66:67], v[70:71], 0, v[66:67]
	ds_read2_b32 v[68:69], v48 offset0:16 offset1:24
	ds_read2_b32 v[72:73], v48 offset0:49 offset1:57
	global_store_dwordx4 v[66:67], v[62:65], off sc1
	ds_read2_b32 v[66:67], v48 offset0:82 offset1:90
	ds_read2_b32 v[74:75], v48 offset0:115 offset1:123
	ds_read2_b32 v[76:77], v48 offset0:148 offset1:156
	ds_read2_b32 v[78:79], v48 offset0:181 offset1:189
	ds_read2_b32 v[80:81], v48 offset0:214 offset1:222
	ds_read2_b32 v[82:83], v48 offset0:247 offset1:255
	s_waitcnt lgkmcnt(7)
	v_mov_b32_e32 v62, v68
	s_waitcnt lgkmcnt(6)
	v_mov_b32_e32 v63, v72
	s_waitcnt lgkmcnt(5)
	v_mov_b32_e32 v64, v66
	s_waitcnt lgkmcnt(4)
	v_mov_b32_e32 v65, v74
	v_pk_mul_f32 v[62:63], v[6:7], v[62:63]
	v_pk_mul_f32 v[64:65], v[8:9], v[64:65]
	v_cvt_pk_bf16_f32 v62, v62, v63
	v_cvt_pk_bf16_f32 v63, v64, v65
	s_waitcnt lgkmcnt(3)
	v_mov_b32_e32 v64, v76
	s_waitcnt lgkmcnt(2)
	v_mov_b32_e32 v65, v78
	v_mov_b32_e32 v72, v69
	v_mov_b32_e32 v74, v67
	v_mov_b32_e32 v78, v77
	v_pk_mul_f32 v[64:65], v[2:3], v[64:65]
	s_waitcnt lgkmcnt(0)
	v_mov_b32_e32 v85, v82
	v_pk_mul_f32 v[6:7], v[6:7], v[72:73]
	v_pk_mul_f32 v[8:9], v[8:9], v[74:75]
	v_pk_mul_f32 v[2:3], v[2:3], v[78:79]
	v_mov_b32_e32 v82, v81
	v_mov_b32_e32 v84, v80
	v_cvt_pk_bf16_f32 v6, v6, v7
	v_cvt_pk_bf16_f32 v7, v8, v9
	v_cvt_pk_bf16_f32 v8, v2, v3
	v_pk_mul_f32 v[2:3], v[4:5], v[82:83]
	v_pk_mul_f32 v[84:85], v[4:5], v[84:85]
	v_or_b32_e32 v15, s38, v50
	v_cvt_pk_bf16_f32 v9, v2, v3
	v_or_b32_e32 v2, s38, v51
	v_cvt_pk_bf16_f32 v64, v64, v65
	v_cvt_pk_bf16_f32 v65, v84, v85
	v_lshlrev_b32_e32 v84, 11, v15
	v_mov_b32_e32 v85, v11
	v_lshlrev_b32_e32 v2, 11, v2
	v_mov_b32_e32 v3, v11
	v_lshl_add_u64 v[84:85], v[70:71], 0, v[84:85]
	v_lshl_add_u64 v[2:3], v[70:71], 0, v[2:3]
	global_store_dwordx4 v[84:85], v[62:65], off sc1
	global_store_dwordx4 v[2:3], v[6:9], off sc1
	s_waitcnt lgkmcnt(0)

; __device__ __forceinline__ void transpose_item(const float* W, int ldw, int Kdim, bf16* WT, int dst_row0, int k0, int n0, LAS float* scr, int lane, const float* gk) {
;     ...
;     for (int i = 0; i < 32; ++i) { const int kk = 2 * i + (lane >> 5); scr[kk * 33 + (lane & 31)] = W[(size_t)(k0 + kk) * ldw + n0 + (lane & 31)]; }
; __global__ void __launch_bounds__(NWAVES * 64, 2) hymba_fwd(Args args_unused) {
;     ...
;             if (r < I_O) { const int nb = D / 32; transpose_item(w_out + (size_t)l * D * D, D, D, WO_T + (size_t)l * D * D, 32 * (r % nb), 64 * (r / nb), 32 * (r % nb), scr, lane, nullptr); continue; } r -= I_O;
.LBB0_22:
	s_andn2_b64 vcc, exec, s[36:37]
	s_cbranch_vccnz .LBB0_24
	s_ashr_i32 s35, s34, 31
	s_lshl_b64 s[36:37], s[34:35], 22
	s_add_u32 s38, s16, s36
	s_addc_u32 s39, s17, s37
	s_lshl_b64 s[36:37], s[34:35], 21
	s_add_u32 s36, s26, s36
	s_addc_u32 s37, s27, s37
	s_lshl_b32 s18, s34, 8
	s_sub_i32 s18, s44, s18
	s_and_b32 s35, s46, 0x3e0
	s_and_b32 s18, s18, 0xfc0
	s_addk_i32 s18, 0xf400
	s_lshl_b32 s40, s35, 2
	s_add_u32 s38, s38, s40
	s_addc_u32 s39, s39, 0
	v_or_b32_e32 v4, s18, v13
	v_mov_b32_e32 v5, v11
	v_or_b32_e32 v6, s18, v16
	v_mov_b32_e32 v7, v11
	v_or_b32_e32 v8, s18, v17
	v_mov_b32_e32 v9, v11
	v_or_b32_e32 v62, s18, v18
	v_mov_b32_e32 v63, v11
	v_or_b32_e32 v64, s18, v19
	v_mov_b32_e32 v65, v11
	v_or_b32_e32 v66, s18, v20
	v_mov_b32_e32 v67, v11
	v_or_b32_e32 v68, s18, v21
	v_mov_b32_e32 v69, v11
	v_or_b32_e32 v70, s18, v22
	v_mov_b32_e32 v71, v11
	v_or_b32_e32 v72, s18, v23
	v_mov_b32_e32 v73, v11
	v_or_b32_e32 v74, s18, v24
	v_mov_b32_e32 v75, v11
	v_or_b32_e32 v76, s18, v25
	v_mov_b32_e32 v77, v11
	v_or_b32_e32 v78, s18, v26
	v_mov_b32_e32 v79, v11
	v_or_b32_e32 v80, s18, v27
	v_mov_b32_e32 v81, v11
	v_or_b32_e32 v82, s18, v28
	v_mov_b32_e32 v83, v11
	v_or_b32_e32 v84, s18, v29
	v_mov_b32_e32 v85, v11
	v_or_b32_e32 v86, s18, v30
	v_mov_b32_e32 v87, v11
	v_or_b32_e32 v88, s18, v31
	v_mov_b32_e32 v89, v11
	v_or_b32_e32 v90, s18, v32
	v_mov_b32_e32 v91, v11
	v_or_b32_e32 v92, s18, v33
	v_mov_b32_e32 v93, v11
	v_or_b32_e32 v94, s18, v34
	v_mov_b32_e32 v95, v11
	v_or_b32_e32 v96, s18, v35
	v_mov_b32_e32 v97, v11
	v_or_b32_e32 v98, s18, v36
	v_mov_b32_e32 v99, v11
	v_or_b32_e32 v100, s18, v37
	v_mov_b32_e32 v101, v11
	v_or_b32_e32 v102, s18, v38
	v_mov_b32_e32 v103, v11
	v_or_b32_e32 v104, s18, v39
	v_mov_b32_e32 v105, v11
	v_or_b32_e32 v106, s18, v40
	v_mov_b32_e32 v107, v11
	v_or_b32_e32 v108, s18, v41
	v_mov_b32_e32 v109, v11
	v_or_b32_e32 v110, s18, v42
	v_mov_b32_e32 v111, v11
	v_or_b32_e32 v112, s18, v43
	v_mov_b32_e32 v113, v11
	v_or_b32_e32 v114, s18, v44
	v_mov_b32_e32 v115, v11
	v_or_b32_e32 v116, s18, v45
	v_mov_b32_e32 v117, v11
	v_or_b32_e32 v118, s18, v46
	v_mov_b32_e32 v119, v11
	v_lshl_add_u64 v[2:3], s[38:39], 0, v[10:11]
	v_lshlrev_b64 v[4:5], 12, v[4:5]
	v_lshlrev_b64 v[6:7], 12, v[6:7]
	v_lshlrev_b64 v[8:9], 12, v[8:9]
	v_lshlrev_b64 v[62:63], 12, v[62:63]
	v_lshlrev_b64 v[64:65], 12, v[64:65]
	v_lshlrev_b64 v[66:67], 12, v[66:67]
	v_lshlrev_b64 v[68:69], 12, v[68:69]
	v_lshlrev_b64 v[70:71], 12, v[70:71]
	v_lshlrev_b64 v[72:73], 12, v[72:73]
	v_lshlrev_b64 v[74:75], 12, v[74:75]
	v_lshlrev_b64 v[76:77], 12, v[76:77]
	v_lshlrev_b64 v[78:79], 12, v[78:79]
	v_lshlrev_b64 v[80:81], 12, v[80:81]
	v_lshlrev_b64 v[82:83], 12, v[82:83]
	v_lshlrev_b64 v[84:85], 12, v[84:85]
	v_lshlrev_b64 v[86:87], 12, v[86:87]
	v_lshlrev_b64 v[88:89], 12, v[88:89]
	v_lshlrev_b64 v[90:91], 12, v[90:91]
	v_lshlrev_b64 v[92:93], 12, v[92:93]
	v_lshlrev_b64 v[94:95], 12, v[94:95]
	v_lshlrev_b64 v[96:97], 12, v[96:97]
	v_lshlrev_b64 v[98:99], 12, v[98:99]
	v_lshlrev_b64 v[100:101], 12, v[100:101]
	v_lshlrev_b64 v[102:103], 12, v[102:103]
	v_lshlrev_b64 v[104:105], 12, v[104:105]
	v_lshlrev_b64 v[106:107], 12, v[106:107]
	v_lshlrev_b64 v[108:109], 12, v[108:109]
	v_lshlrev_b64 v[110:111], 12, v[110:111]
	v_lshlrev_b64 v[112:113], 12, v[112:113]
	v_lshlrev_b64 v[114:115], 12, v[114:115]
	v_lshlrev_b64 v[116:117], 12, v[116:117]
	v_lshlrev_b64 v[118:119], 12, v[118:119]
	v_lshl_add_u64 v[4:5], v[2:3], 0, v[4:5]
	v_lshl_add_u64 v[6:7], v[2:3], 0, v[6:7]
	v_lshl_add_u64 v[8:9], v[2:3], 0, v[8:9]
	v_lshl_add_u64 v[62:63], v[2:3], 0, v[62:63]
	v_lshl_add_u64 v[64:65], v[2:3], 0, v[64:65]
	v_lshl_add_u64 v[66:67], v[2:3], 0, v[66:67]
	v_lshl_add_u64 v[68:69], v[2:3], 0, v[68:69]
	v_lshl_add_u64 v[70:71], v[2:3], 0, v[70:71]
	v_lshl_add_u64 v[72:73], v[2:3], 0, v[72:73]
	v_lshl_add_u64 v[74:75], v[2:3], 0, v[74:75]
	v_lshl_add_u64 v[76:77], v[2:3], 0, v[76:77]
	v_lshl_add_u64 v[78:79], v[2:3], 0, v[78:79]
	v_lshl_add_u64 v[80:81], v[2:3], 0, v[80:81]
	v_lshl_add_u64 v[82:83], v[2:3], 0, v[82:83]
	v_lshl_add_u64 v[84:85], v[2:3], 0, v[84:85]
	v_lshl_add_u64 v[86:87], v[2:3], 0, v[86:87]
	v_lshl_add_u64 v[88:89], v[2:3], 0, v[88:89]
	v_lshl_add_u64 v[90:91], v[2:3], 0, v[90:91]
	v_lshl_add_u64 v[92:93], v[2:3], 0, v[92:93]
	v_lshl_add_u64 v[94:95], v[2:3], 0, v[94:95]
	v_lshl_add_u64 v[96:97], v[2:3], 0, v[96:97]
	v_lshl_add_u64 v[98:99], v[2:3], 0, v[98:99]
	v_lshl_add_u64 v[100:101], v[2:3], 0, v[100:101]
	v_lshl_add_u64 v[102:103], v[2:3], 0, v[102:103]
	v_lshl_add_u64 v[104:105], v[2:3], 0, v[104:105]
	v_lshl_add_u64 v[106:107], v[2:3], 0, v[106:107]
	v_lshl_add_u64 v[108:109], v[2:3], 0, v[108:109]
	v_lshl_add_u64 v[110:111], v[2:3], 0, v[110:111]
	v_lshl_add_u64 v[112:113], v[2:3], 0, v[112:113]
	v_lshl_add_u64 v[114:115], v[2:3], 0, v[114:115]
	v_lshl_add_u64 v[116:117], v[2:3], 0, v[116:117]
	v_lshl_add_u64 v[2:3], v[2:3], 0, v[118:119]
	global_load_dword v4, v[4:5], off
	s_nop 0
	global_load_dword v5, v[6:7], off
	s_nop 0
	global_load_dword v6, v[8:9], off
	global_load_dword v7, v[62:63], off
	s_nop 0
	global_load_dword v8, v[64:65], off
	global_load_dword v9, v[66:67], off
	global_load_dword v15, v[68:69], off
	global_load_dword v62, v[70:71], off
	global_load_dword v63, v[72:73], off
	s_nop 0
	global_load_dword v64, v[74:75], off
	global_load_dword v65, v[76:77], off
	global_load_dword v66, v[78:79], off
	global_load_dword v67, v[80:81], off
	global_load_dword v68, v[82:83], off
	global_load_dword v69, v[84:85], off
	global_load_dword v70, v[86:87], off
	global_load_dword v71, v[88:89], off
	global_load_dword v72, v[90:91], off
	global_load_dword v73, v[92:93], off
	global_load_dword v74, v[94:95], off
	global_load_dword v75, v[96:97], off
	global_load_dword v76, v[98:99], off
	global_load_dword v77, v[100:101], off
	global_load_dword v78, v[102:103], off
	global_load_dword v79, v[104:105], off
	global_load_dword v80, v[106:107], off
	global_load_dword v81, v[108:109], off
	global_load_dword v82, v[110:111], off
	global_load_dword v83, v[112:113], off
	global_load_dword v84, v[114:115], off
	global_load_dword v85, v[116:117], off
	s_nop 0
	global_load_dword v2, v[2:3], off
	s_waitcnt vmcnt(30)
; #define GAS __attribute__((address_space(1)))
; #define LAS __attribute__((address_space(3)))
; #define LDS_WAIT() asm volatile("s_waitcnt lgkmcnt(0)" ::: "memory")
; __device__ __forceinline__ unsigned pk2(float lo, float hi) { const f32x2_fr v = {lo, hi}; return __builtin_bit_cast(unsigned, __builtin_convertvector(v, bf16x2_fr)); }
; __device__ __forceinline__ void transpose_item(const float* W, int ldw, int Kdim, bf16* WT, int dst_row0, int k0, int n0, LAS float* scr, int lane, const float* gk) {
; #pragma unroll
;     for (int i = 0; i < 32; ++i) { const int kk = 2 * i + (lane >> 5); scr[kk * 33 + (lane & 31)] = W[(size_t)(k0 + kk) * ldw + n0 + (lane & 31)]; }
;     LDS_WAIT(); asm volatile("" ::: "memory");
;     const int c = lane & 7;
;     f32x4 ga = {1.f, 1.f, 1.f, 1.f}, gb = ga; if (gk) { ga = *(const f32x4*)(gk + k0 + 8 * c); gb = *(const f32x4*)(gk + k0 + 8 * c + 4); }
; #pragma unroll
;     for (int j = 0; j < 4; ++j) { const int n = (lane >> 3) + 8 * j; const LAS float* s = scr + (8 * c) * 33 + n;
;         v4u o; o.x = pk2(s[0 * 33] * ga.x, s[1 * 33] * ga.y); o.y = pk2(s[2 * 33] * ga.z, s[3 * 33] * ga.w); o.z = pk2(s[4 * 33] * gb.x, s[5 * 33] * gb.y); o.w = pk2(s[6 * 33] * gb.z, s[7 * 33] * gb.w);
;         *(GAS v4u*)(WT + (size_t)(dst_row0 + n) * Kdim + k0 + 8 * c) = o; }
;     LDS_WAIT(); asm volatile("" ::: "memory");
; }
	ds_write2_b32 v52, v4, v5 offset1:66
	s_waitcnt vmcnt(28)
	ds_write2_b32 v52, v6, v7 offset0:132 offset1:198
	s_waitcnt vmcnt(26)
	ds_write2_b32 v56, v8, v9 offset0:8 offset1:74
	s_waitcnt vmcnt(24)
	ds_write2_b32 v53, v15, v62 offset1:66
	s_waitcnt vmcnt(22)
	ds_write2_b32 v53, v63, v64 offset0:132 offset1:198
	s_waitcnt vmcnt(20)
	ds_write2_b32 v57, v65, v66 offset0:8 offset1:74
	s_waitcnt vmcnt(18)
	ds_write2_b32 v54, v67, v68 offset1:66
	s_waitcnt vmcnt(16)
	ds_write2_b32 v54, v69, v70 offset0:132 offset1:198
	s_waitcnt vmcnt(14)
	ds_write2_b32 v58, v71, v72 offset0:8 offset1:74
	s_waitcnt vmcnt(12)
	ds_write2_b32 v55, v73, v74 offset1:66
	s_waitcnt vmcnt(10)
	ds_write2_b32 v55, v75, v76 offset0:132 offset1:198
	s_waitcnt vmcnt(8)
	ds_write2_b32 v59, v77, v78 offset0:8 offset1:74
	s_waitcnt vmcnt(6)
	ds_write2_b32 v59, v79, v80 offset0:140 offset1:206
	s_waitcnt vmcnt(4)
	ds_write2_b32 v60, v81, v82 offset0:16 offset1:82
	s_waitcnt vmcnt(2)
	ds_write2_b32 v60, v83, v84 offset0:148 offset1:214
	s_waitcnt vmcnt(0)
	ds_write2_b32 v61, v85, v2 offset0:24 offset1:90
	s_waitcnt lgkmcnt(0)
	ds_read2_b32 v[6:7], v48 offset0:33 offset1:41
	ds_read2_b32 v[8:9], v48 offset1:8
	ds_read2_b32 v[62:63], v48 offset0:66 offset1:74
	ds_read2_b32 v[64:65], v48 offset0:99 offset1:107
	ds_read2_b32 v[66:67], v48 offset0:132 offset1:140
	ds_read2_b32 v[68:69], v48 offset0:165 offset1:173
	ds_read2_b32 v[70:71], v48 offset0:198 offset1:206
	ds_read2_b32 v[72:73], v48 offset0:231 offset1:239
	s_lshl_b64 s[38:39], s[18:19], 1
	s_add_u32 s36, s36, s38
	s_addc_u32 s37, s37, s39
	v_mov_b32_e32 v15, v11
	s_waitcnt lgkmcnt(6)
	v_cvt_pk_bf16_f32 v2, v8, v6
	v_or_b32_e32 v6, s35, v47
	v_lshl_add_u64 v[74:75], s[36:37], 0, v[14:15]
	v_lshlrev_b32_e32 v76, 11, v6
	v_mov_b32_e32 v77, v11
	s_waitcnt lgkmcnt(4)
	v_cvt_pk_bf16_f32 v3, v62, v64
	s_waitcnt lgkmcnt(2)
	v_cvt_pk_bf16_f32 v4, v66, v68
	s_waitcnt lgkmcnt(0)
	v_cvt_pk_bf16_f32 v5, v70, v72
	v_lshl_add_u64 v[76:77], v[74:75], 0, v[76:77]
	global_store_dwordx4 v[76:77], v[2:5], off sc1
	v_or_b32_e32 v6, s35, v49
	v_lshlrev_b32_e32 v6, 11, v6
	v_cvt_pk_bf16_f32 v2, v9, v7
	v_cvt_pk_bf16_f32 v3, v63, v65
	v_cvt_pk_bf16_f32 v4, v67, v69
	v_cvt_pk_bf16_f32 v5, v71, v73
	ds_read2_b32 v[8:9], v48 offset0:49 offset1:57
	ds_read2_b32 v[62:63], v48 offset0:16 offset1:24
	ds_read2_b32 v[64:65], v48 offset0:82 offset1:90
	ds_read2_b32 v[66:67], v48 offset0:115 offset1:123
	ds_read2_b32 v[68:69], v48 offset0:148 offset1:156
	ds_read2_b32 v[70:71], v48 offset0:181 offset1:189
	ds_read2_b32 v[72:73], v48 offset0:214 offset1:222
	ds_read2_b32 v[76:77], v48 offset0:247 offset1:255
	v_mov_b32_e32 v7, v11
	v_lshl_add_u64 v[6:7], v[74:75], 0, v[6:7]
	global_store_dwordx4 v[6:7], v[2:5], off sc1
	v_or_b32_e32 v6, s35, v50
	v_lshlrev_b32_e32 v6, 11, v6
	v_mov_b32_e32 v7, v11
	s_waitcnt lgkmcnt(6)
	v_cvt_pk_bf16_f32 v2, v62, v8
	s_waitcnt lgkmcnt(4)
	v_cvt_pk_bf16_f32 v3, v64, v66
	s_waitcnt lgkmcnt(2)
	v_cvt_pk_bf16_f32 v4, v68, v70
	s_waitcnt lgkmcnt(0)
	v_cvt_pk_bf16_f32 v5, v72, v76
	v_lshl_add_u64 v[6:7], v[74:75], 0, v[6:7]
	global_store_dwordx4 v[6:7], v[2:5], off sc1
	v_or_b32_e32 v6, s35, v51
	v_lshlrev_b32_e32 v6, 11, v6
	v_mov_b32_e32 v7, v11
	v_cvt_pk_bf16_f32 v2, v63, v9
	v_cvt_pk_bf16_f32 v3, v65, v67
	v_cvt_pk_bf16_f32 v4, v69, v71
	v_cvt_pk_bf16_f32 v5, v73, v77
	v_lshl_add_u64 v[6:7], v[74:75], 0, v[6:7]
	global_store_dwordx4 v[6:7], v[2:5], off sc1
	s_waitcnt lgkmcnt(0)

; #define LAS __attribute__((address_space(3)))
; __device__ __forceinline__ unsigned pk2(float lo, float hi) { const f32x2_fr v = {lo, hi}; return __builtin_bit_cast(unsigned, __builtin_convertvector(v, bf16x2_fr)); }
; __device__ __forceinline__ float row_rstd(const f32x4 (&v)[4]) {
;     float s = 0.f;
; #pragma unroll
;     for (int j = 0; j < 4; ++j) s += (v[j].x * v[j].x + v[j].y * v[j].y) + (v[j].z * v[j].z + v[j].w * v[j].w);
;     return __builtin_amdgcn_rsqf(wave_sum(s) * (1.0f / D) + EPS);
; }
; __device__ __forceinline__ void store_row_bf16(bf16* p, int lane, const f32x4 (&v)[4]) {
;     v2u* o = (v2u*)p + lane;
; #pragma unroll
;     for (int j = 0; j < 4; ++j) { v2u w; w.x = pk2(v[j].x, v[j].y); w.y = pk2(v[j].z, v[j].w); o[64 * j] = w; }
; }
; __device__ __forceinline__ void fill_forget_w(const float* win_l, LAS unsigned char* ldsl, int tid) {
;     LAS float* wfl = (LAS float*)(ldsl + WFL_OFF);
;     for (int idx = tid; idx < 8 * D; idx += NWAVES * 64) { const int k = idx >> 3, f = idx & 7; wfl[f * D + k] = win_l[(size_t)k * INW + NQKV + f]; }
;     __syncthreads();
; }
; __device__ __forceinline__ void pre_norm_row(const f32x4 (&xv)[4], const f32x4 (&g)[4], bf16* xb_row, const LAS float* wfl, const float* fbias, float* logf, float* rs, int row, int lane) {
;     const float rstd = row_rstd(xv); f32x4 h[4];
; #pragma unroll
;     for (int j = 0; j < 4; ++j) h[j] = xv[j] * rstd * g[j];
;     if (xb_row) store_row_bf16(xb_row, lane, xv);
;     if (lane == 0) rs[row] = rstd;
; __global__ void __launch_bounds__(NWAVES * 64, 2) hymba_fwd(Args args_unused) {
;     ...
;             f32x4 xv[4]; load_row_nt(x_in + (size_t)gw * D, lane, xv);
;             for (int m = gw; m < M; m += NGW) { f32x4 xn[4]; const int mn = (m + NGW < M) ? m + NGW : m; load_row_nt(x_in + (size_t)mn * D, lane, xn);
;                 pre_norm_row(xv, g, XN + (size_t)m * D, (const LAS float*)(ldsl + WFL_OFF), fbias, LOGF, (float*)(A->ws + WS_RS1), m, lane);
.LBB0_55:
	s_mov_b32 s38, s34
	s_add_i32 s34, s34, s28
	s_cmpk_gt_i32 s34, 0x7fff
	s_cselect_b64 s[22:23], -1, 0
	s_cmp_lt_i32 s34, 0x8000
	s_cselect_b32 s40, s34, s38
	s_ashr_i32 s41, s40, 31
	s_lshl_b64 s[40:41], s[40:41], 12
	v_lshl_add_u64 v[158:159], v[180:181], 0, s[40:41]
	global_load_dwordx4 v[146:149], v[158:159], off nt
	global_load_dwordx4 v[150:153], v[158:159], off offset:1024 nt
	global_load_dwordx4 v[154:157], v[158:159], off offset:2048 nt
	s_nop 0
	global_load_dwordx4 v[158:161], v[158:159], off offset:3072 nt
	s_waitcnt vmcnt(4)
	v_mul_f32_e32 v178, v175, v175
	v_mul_f32_e32 v189, v177, v177
	v_fmac_f32_e32 v178, v174, v174
	v_fmac_f32_e32 v189, v176, v176
	v_add_f32_e32 v178, v178, v189
	v_mul_f32_e32 v189, v171, v171
	v_mul_f32_e32 v190, v173, v173
	v_fmac_f32_e32 v189, v170, v170
	v_fmac_f32_e32 v190, v172, v172
	v_add_f32_e32 v189, v189, v190
	v_add_f32_e32 v178, v178, v189
	v_mul_f32_e32 v189, v167, v167
	v_mul_f32_e32 v190, v169, v169
	v_fmac_f32_e32 v189, v166, v166
	v_fmac_f32_e32 v190, v168, v168
	v_add_f32_e32 v189, v189, v190
	v_add_f32_e32 v178, v178, v189
	v_mul_f32_e32 v189, v163, v163
	v_mul_f32_e32 v190, v165, v165
	v_fmac_f32_e32 v189, v162, v162
	v_fmac_f32_e32 v190, v164, v164
	v_add_f32_e32 v189, v189, v190
	v_add_f32_e32 v178, v178, v189
	s_ashr_i32 s39, s38, 31
	s_lshl_b64 s[40:41], s[38:39], 11
	v_add_f32_dpp v178, v178, v178 quad_perm:[1,0,3,2] row_mask:0xf bank_mask:0xf bound_ctrl:1
	v_lshl_add_u64 v[190:191], v[182:183], 0, s[40:41]
	v_cvt_pk_bf16_f32 v192, v174, v175
	v_add_f32_dpp v178, v178, v178 quad_perm:[2,3,0,1] row_mask:0xf bank_mask:0xf bound_ctrl:1
	v_cvt_pk_bf16_f32 v193, v176, v177
	global_store_dwordx2 v[190:191], v[192:193], off sc1
	v_add_f32_dpp v178, v178, v178 row_ror:4 row_mask:0xf bank_mask:0xf bound_ctrl:1
	v_cvt_pk_bf16_f32 v192, v170, v171
	v_cvt_pk_bf16_f32 v193, v172, v173
	v_add_f32_dpp v178, v178, v178 row_ror:8 row_mask:0xf bank_mask:0xf bound_ctrl:1
	v_mov_b32_e32 v189, v178
	s_nop 1
	v_permlane16_swap_b32_e32 v178, v189
	v_add_f32_e32 v178, v178, v189
	v_mov_b32_e32 v189, v178
	s_nop 1
	v_permlane32_swap_b32_e32 v178, v189
	v_add_f32_e32 v178, v178, v189
	v_fmamk_f32 v178, v178, 0x3a800000, v187
	v_rsq_f32_e32 v178, v178
	global_store_dwordx2 v[190:191], v[192:193], off offset:512 sc1
	v_cvt_pk_bf16_f32 v192, v166, v167
	v_cvt_pk_bf16_f32 v193, v168, v169
	global_store_dwordx2 v[190:191], v[192:193], off offset:1024 sc1
	v_cvt_pk_bf16_f32 v192, v162, v163
	v_cvt_pk_bf16_f32 v193, v164, v165
	global_store_dwordx2 v[190:191], v[192:193], off offset:1536 sc1
	s_and_saveexec_b64 s[40:41], s[20:21]
	s_cbranch_execz .LBB0_57
	s_lshl_b64 s[42:43], s[38:39], 2
	s_add_u32 s42, s1, s42
	s_addc_u32 s43, s2, s43
	global_store_dword v179, v178, s[42:43]

; __device__ __forceinline__ unsigned pk2(float lo, float hi) { const f32x2_fr v = {lo, hi}; return __builtin_bit_cast(unsigned, __builtin_convertvector(v, bf16x2_fr)); }
; __device__ __forceinline__ float row_rstd(const f32x4 (&v)[4]) {
;     float s = 0.f;
; #pragma unroll
;     for (int j = 0; j < 4; ++j) s += (v[j].x * v[j].x + v[j].y * v[j].y) + (v[j].z * v[j].z + v[j].w * v[j].w);
;     return __builtin_amdgcn_rsqf(wave_sum(s) * (1.0f / D) + EPS);
; }
; __device__ __forceinline__ void store_row_bf16(bf16* p, int lane, const f32x4 (&v)[4]) {
;     v2u* o = (v2u*)p + lane;
; #pragma unroll
;     for (int j = 0; j < 4; ++j) { v2u w; w.x = pk2(v[j].x, v[j].y); w.y = pk2(v[j].z, v[j].w); o[64 * j] = w; }
; }
; __global__ void __launch_bounds__(NWAVES * 64, 2) hymba_fwd(Args args_unused) {
;     ...
;             for (int m = gw; m < M; m += NGW) { f32x4 yn[4], xn[4];
;                 const int mn = (m + NGW < M) ? m + NGW : m;
;                 load_row_bf16_nt(Y1 + (size_t)mn * D, lane, yn); if (l == 0) load_row_nt(x_in + (size_t)mn * D, lane, xn); else load_row_bf16(XB + (size_t)mn * D, lane, xn);
;                 const float ry = row_rstd(y);
; #pragma unroll
;                 for (int j = 0; j < 4; ++j) xv[j] += y[j] * ry * gp[j];
;                 store_row_bf16(XB + (size_t)m * D, lane, xv);
;                 const float rx = row_rstd(xv);
;                 if (lane == 0) RS2[m] = rx;
; #pragma unroll
;                 for (int j = 0; j < 4; ++j) { y[j] = yn[j]; xv[j] = xn[j]; }
;             }
.LBB0_558:
	v_mul_f32_e32 v0, v71, v71
	v_mul_f32_e32 v82, v73, v73
	v_fmac_f32_e32 v0, v70, v70
	v_fmac_f32_e32 v82, v72, v72
	v_add_f32_e32 v0, v0, v82
	v_mul_f32_e32 v82, v67, v67
	v_mul_f32_e32 v83, v69, v69
	v_fmac_f32_e32 v82, v66, v66
	v_fmac_f32_e32 v83, v68, v68
	v_add_f32_e32 v82, v82, v83
	v_add_f32_e32 v0, v0, v82
	v_mul_f32_e32 v82, v63, v63
	v_mul_f32_e32 v83, v65, v65
	v_fmac_f32_e32 v82, v62, v62
	v_fmac_f32_e32 v83, v64, v64
	v_add_f32_e32 v82, v82, v83
	v_add_f32_e32 v0, v0, v82
	v_mul_f32_e32 v82, v59, v59
	v_mul_f32_e32 v83, v61, v61
	v_fmac_f32_e32 v82, v58, v58
	v_fmac_f32_e32 v83, v60, v60
	v_add_f32_e32 v82, v82, v83
	v_add_f32_e32 v0, v0, v82
	s_nop 1
	v_add_f32_dpp v0, v0, v0 quad_perm:[1,0,3,2] row_mask:0xf bank_mask:0xf bound_ctrl:1
	s_nop 1
	v_add_f32_dpp v0, v0, v0 quad_perm:[2,3,0,1] row_mask:0xf bank_mask:0xf bound_ctrl:1
	s_nop 1
	v_add_f32_dpp v0, v0, v0 row_ror:4 row_mask:0xf bank_mask:0xf bound_ctrl:1
	s_nop 1
	v_add_f32_dpp v0, v0, v0 row_ror:8 row_mask:0xf bank_mask:0xf bound_ctrl:1
	v_mov_b32_e32 v82, v0
	s_nop 1
	v_permlane16_swap_b32_e32 v0, v82
	v_add_f32_e32 v0, v0, v82
	v_mov_b32_e32 v82, v0
	s_nop 1
	v_permlane32_swap_b32_e32 v0, v82
	v_add_f32_e32 v0, v0, v82
	v_fmamk_f32 v0, v0, 0x3a800000, v249
	v_rsq_f32_e32 v0, v0
	s_nop 0
	v_pk_mul_f32 v[70:71], v[0:1], v[70:71] op_sel_hi:[0,1]
	v_pk_mul_f32 v[72:73], v[0:1], v[72:73] op_sel_hi:[0,1]
	v_pk_fma_f32 v[2:3], v[70:71], v[34:35], v[2:3]
	v_pk_fma_f32 v[4:5], v[72:73], v[36:37], v[4:5]
	v_pk_mul_f32 v[66:67], v[0:1], v[66:67] op_sel_hi:[0,1]
	v_pk_mul_f32 v[68:69], v[0:1], v[68:69] op_sel_hi:[0,1]
	v_pk_mul_f32 v[62:63], v[0:1], v[62:63] op_sel_hi:[0,1]
	v_pk_mul_f32 v[64:65], v[0:1], v[64:65] op_sel_hi:[0,1]
	v_pk_mul_f32 v[58:59], v[0:1], v[58:59] op_sel_hi:[0,1]
	v_pk_mul_f32 v[60:61], v[0:1], v[60:61] op_sel_hi:[0,1]
	v_mul_f32_e32 v0, v3, v3
	v_pk_fma_f32 v[14:15], v[58:59], v[46:47], v[14:15]
	v_cvt_pk_bf16_f32 v58, v2, v3
	v_fmac_f32_e32 v0, v2, v2
	v_mul_f32_e32 v2, v5, v5
	v_pk_fma_f32 v[8:9], v[68:69], v[40:41], v[8:9]
	v_pk_fma_f32 v[6:7], v[66:67], v[38:39], v[6:7]
	v_fmac_f32_e32 v2, v4, v4
	v_add_f32_e32 v0, v0, v2
	v_mul_f32_e32 v2, v7, v7
	v_mul_f32_e32 v3, v9, v9
	v_fmac_f32_e32 v2, v6, v6
	v_fmac_f32_e32 v3, v8, v8
	v_pk_fma_f32 v[12:13], v[64:65], v[44:45], v[12:13]
	v_pk_fma_f32 v[10:11], v[62:63], v[42:43], v[10:11]
	v_add_f32_e32 v2, v2, v3
	v_add_f32_e32 v0, v0, v2
	v_mul_f32_e32 v2, v11, v11
	v_mul_f32_e32 v3, v13, v13
	v_fmac_f32_e32 v2, v10, v10
	v_fmac_f32_e32 v3, v12, v12
	v_pk_fma_f32 v[16:17], v[60:61], v[48:49], v[16:17]
	v_add_f32_e32 v2, v2, v3
	v_add_f32_e32 v0, v2, v0
	v_mul_f32_e32 v2, v15, v15
	v_mul_f32_e32 v3, v17, v17
	v_fmac_f32_e32 v2, v14, v14
	v_fmac_f32_e32 v3, v16, v16
	v_add_f32_e32 v2, v2, v3
	v_add_f32_e32 v0, v2, v0
	v_cvt_pk_bf16_f32 v59, v4, v5
	global_store_dwordx2 v[56:57], v[58:59], off offset:-1024 sc1
	v_add_f32_dpp v0, v0, v0 quad_perm:[1,0,3,2] row_mask:0xf bank_mask:0xf bound_ctrl:1
	v_cvt_pk_bf16_f32 v58, v6, v7
	v_cvt_pk_bf16_f32 v59, v8, v9
	v_add_f32_dpp v0, v0, v0 quad_perm:[2,3,0,1] row_mask:0xf bank_mask:0xf bound_ctrl:1
	global_store_dwordx2 v[56:57], v[58:59], off offset:-512 sc1
	v_cvt_pk_bf16_f32 v58, v10, v11
	v_add_f32_dpp v0, v0, v0 row_ror:4 row_mask:0xf bank_mask:0xf bound_ctrl:1
	v_cvt_pk_bf16_f32 v59, v12, v13
	global_store_dwordx2 v[56:57], v[58:59], off sc1
	v_add_f32_dpp v0, v0, v0 row_ror:8 row_mask:0xf bank_mask:0xf bound_ctrl:1
	v_mov_b32_e32 v2, v0
	s_nop 1
	v_permlane16_swap_b32_e32 v0, v2
	v_add_f32_e32 v0, v0, v2
	v_mov_b32_e32 v2, v0
	v_cvt_pk_bf16_f32 v58, v14, v15
	v_cvt_pk_bf16_f32 v59, v16, v17
	v_permlane32_swap_b32_e32 v0, v2
	global_store_dwordx2 v[56:57], v[58:59], off offset:512 sc1
	s_and_saveexec_b64 s[14:15], s[4:5]
	s_cbranch_execz .LBB0_553
	v_add_f32_e32 v0, v0, v2
	v_fmamk_f32 v0, v0, 0x3a800000, v249
	v_rsq_f32_e32 v0, v0
	global_store_dword v1, v0, s[10:11]
	s_branch .LBB0_553

; __global__ void __launch_bounds__(NWAVES * 64, 2) hymba_fwd(Args args_unused) {
;     ...
;                 for (int m = gw; m < M; m += NGW) { f32x4 yn[4], xn[4];
;                     const int mn = (m + NGW < M) ? m + NGW : m;
;                     load_row_bf16_nt(Y2 + (size_t)mn * D, lane, yn); load_row_bf16(XB + (size_t)mn * D, lane, xn);
;                     const float ry = row_rstd(y);
; #pragma unroll
;                     for (int j = 0; j < 4; ++j) xv[j] += y[j] * ry * gp[j];
;                     store_row(xout + (size_t)m * D, lane, xv);
; #pragma unroll
;                     for (int j = 0; j < 4; ++j) { y[j] = yn[j]; xv[j] = xn[j]; }
;                 }
.LBB0_768:
	s_add_i32 s1, s0, s28
	s_cmp_lt_i32 s1, 0x8000
	s_cselect_b64 s[2:3], -1, 0
	s_and_b64 vcc, s[2:3], exec
	s_cselect_b32 s8, s1, s0
	v_mul_f32_e32 v0, v59, v59
	v_mul_f32_e32 v19, v61, v61
	v_mul_f32_e32 v21, v55, v55
	v_mul_f32_e32 v35, v57, v57
	v_mul_f32_e32 v62, v51, v51
	v_mul_f32_e32 v63, v53, v53
	v_mul_f32_e32 v64, v47, v47
	v_mul_f32_e32 v65, v49, v49
	s_ashr_i32 s9, s8, 31
	v_fmac_f32_e32 v0, v58, v58
	v_fmac_f32_e32 v19, v60, v60
	v_fmac_f32_e32 v21, v54, v54
	v_fmac_f32_e32 v35, v56, v56
	v_fmac_f32_e32 v62, v50, v50
	v_fmac_f32_e32 v63, v52, v52
	v_fmac_f32_e32 v64, v46, v46
	v_fmac_f32_e32 v65, v48, v48
	s_lshl_b64 s[2:3], s[8:9], 11
	v_add_f32_e32 v0, v0, v19
	v_add_f32_e32 v19, v21, v35
	v_add_f32_e32 v21, v62, v63
	v_add_f32_e32 v35, v64, v65
	v_lshl_add_u64 v[62:63], v[22:23], 0, s[2:3]
	v_lshl_add_u64 v[64:65], v[24:25], 0, s[2:3]
	global_load_dwordx2 v[66:67], v[62:63], off nt
	global_load_dwordx2 v[68:69], v[62:63], off offset:512 nt
	global_load_dwordx2 v[70:71], v[62:63], off offset:1024 nt
	s_nop 0
	global_load_dwordx2 v[62:63], v[62:63], off offset:1536 nt
	s_nop 0
	global_load_dwordx2 v[72:73], v[64:65], off
	global_load_dwordx2 v[74:75], v[64:65], off offset:512
	global_load_dwordx2 v[76:77], v[64:65], off offset:1024
	s_nop 0
	global_load_dwordx2 v[64:65], v[64:65], off offset:1536
	v_add_f32_e32 v0, v0, v19
	v_add_f32_e32 v0, v0, v21
	v_add_f32_e32 v0, v0, v35
	s_mov_b32 s0, s1
	s_nop 0
	v_add_f32_dpp v0, v0, v0 quad_perm:[1,0,3,2] row_mask:0xf bank_mask:0xf bound_ctrl:1
	s_nop 1
	v_add_f32_dpp v0, v0, v0 quad_perm:[2,3,0,1] row_mask:0xf bank_mask:0xf bound_ctrl:1
	s_nop 1
	v_add_f32_dpp v0, v0, v0 row_ror:4 row_mask:0xf bank_mask:0xf bound_ctrl:1
	s_nop 1
	v_add_f32_dpp v0, v0, v0 row_ror:8 row_mask:0xf bank_mask:0xf bound_ctrl:1
	v_mov_b32_e32 v19, v0
	s_nop 1
	v_permlane16_swap_b32_e32 v0, v19
	v_add_f32_e32 v0, v0, v19
	v_mov_b32_e32 v19, v0
	s_nop 1
	v_permlane32_swap_b32_e32 v0, v19
	v_add_f32_e32 v0, v0, v19
	v_fmamk_f32 v0, v0, 0x3a800000, v249
	v_rsq_f32_e32 v0, v0
	s_nop 0
	v_pk_mul_f32 v[58:59], v[0:1], v[58:59] op_sel_hi:[0,1]
	v_pk_mul_f32 v[60:61], v[0:1], v[60:61] op_sel_hi:[0,1]
	v_pk_mul_f32 v[54:55], v[0:1], v[54:55] op_sel_hi:[0,1]
	v_pk_mul_f32 v[56:57], v[0:1], v[56:57] op_sel_hi:[0,1]
	v_pk_mul_f32 v[78:79], v[0:1], v[46:47] op_sel_hi:[0,1]
	v_pk_mul_f32 v[80:81], v[0:1], v[48:49] op_sel_hi:[0,1]
	v_pk_mul_f32 v[50:51], v[0:1], v[50:51] op_sel_hi:[0,1]
	v_pk_mul_f32 v[52:53], v[0:1], v[52:53] op_sel_hi:[0,1]
	v_pk_fma_f32 v[30:31], v[60:61], v[4:5], v[30:31]
	v_pk_fma_f32 v[28:29], v[58:59], v[2:3], v[28:29]
	v_pk_fma_f32 v[48:49], v[56:57], v[8:9], v[36:37]
	v_pk_fma_f32 v[46:47], v[54:55], v[6:7], v[32:33]
	v_pk_fma_f32 v[44:45], v[80:81], v[16:17], v[44:45]
	v_pk_fma_f32 v[42:43], v[78:79], v[14:15], v[42:43]
	v_pk_fma_f32 v[40:41], v[52:53], v[12:13], v[40:41]
	v_pk_fma_f32 v[38:39], v[50:51], v[10:11], v[38:39]
	global_store_dwordx4 v[26:27], v[28:31], off offset:-2048 sc1
	global_store_dwordx4 v[26:27], v[46:49], off offset:-1024 sc1
	global_store_dwordx4 v[26:27], v[38:41], off sc1
	global_store_dwordx4 v[26:27], v[42:45], off offset:1024 sc1
	v_lshl_add_u64 v[26:27], v[26:27], 0, s[78:79]
	s_waitcnt vmcnt(11)
	v_lshlrev_b32_e32 v58, 16, v66
	v_and_b32_e32 v59, 0xffff0000, v66
	v_lshlrev_b32_e32 v60, 16, v67
	v_and_b32_e32 v61, 0xffff0000, v67
	s_waitcnt vmcnt(10)
	v_lshlrev_b32_e32 v54, 16, v68
	v_and_b32_e32 v55, 0xffff0000, v68
	v_lshlrev_b32_e32 v56, 16, v69
	v_and_b32_e32 v57, 0xffff0000, v69
	s_waitcnt vmcnt(9)
	v_lshlrev_b32_e32 v50, 16, v70
	v_and_b32_e32 v51, 0xffff0000, v70
	v_lshlrev_b32_e32 v52, 16, v71
	v_and_b32_e32 v53, 0xffff0000, v71
	s_waitcnt vmcnt(8)
	v_lshlrev_b32_e32 v46, 16, v62
	v_and_b32_e32 v47, 0xffff0000, v62
	v_lshlrev_b32_e32 v48, 16, v63
	v_and_b32_e32 v49, 0xffff0000, v63
	s_waitcnt vmcnt(7)
	v_lshlrev_b32_e32 v42, 16, v72
	v_and_b32_e32 v43, 0xffff0000, v72
	v_lshlrev_b32_e32 v44, 16, v73
	v_and_b32_e32 v45, 0xffff0000, v73
	s_waitcnt vmcnt(6)
	v_lshlrev_b32_e32 v62, 16, v74
	v_and_b32_e32 v63, 0xffff0000, v74
	v_lshlrev_b32_e32 v66, 16, v75
	v_and_b32_e32 v67, 0xffff0000, v75
	s_waitcnt vmcnt(5)
	v_lshlrev_b32_e32 v68, 16, v76
	v_and_b32_e32 v69, 0xffff0000, v76
	v_lshlrev_b32_e32 v70, 16, v77
	v_and_b32_e32 v71, 0xffff0000, v77
	s_waitcnt vmcnt(4)
	v_lshlrev_b32_e32 v72, 16, v64
	v_and_b32_e32 v64, 0xffff0000, v64
	v_lshlrev_b32_e32 v73, 16, v65
	v_and_b32_e32 v65, 0xffff0000, v65
	v_mov_b32_e32 v28, v42
	v_mov_b32_e32 v29, v43
	v_mov_b32_e32 v30, v44
	v_mov_b32_e32 v31, v45
	v_mov_b32_e32 v32, v62
	v_mov_b32_e32 v33, v63
	v_mov_b32_e32 v36, v66
	v_mov_b32_e32 v37, v67
	v_mov_b32_e32 v38, v68
	v_mov_b32_e32 v39, v69
	v_mov_b32_e32 v40, v70
	v_mov_b32_e32 v41, v71
	v_mov_b32_e32 v42, v72
	v_mov_b32_e32 v43, v64
	v_mov_b32_e32 v44, v73
	v_mov_b32_e32 v45, v65
	s_cbranch_vccnz .LBB0_768

; __global__ void __launch_bounds__(NWAVES * 64, 2) hymba_fwd(Args args_unused) {
;     ...
;             for (int m = gw; m < M; m += NGW) { f32x4 yn[4], xn[4];
;                 const int mn = (m + NGW < M) ? m + NGW : m;
;                 load_row_bf16_nt(Y1 + (size_t)mn * D, lane, yn); if (l == 0) load_row_nt(x_in + (size_t)mn * D, lane, xn); else load_row_bf16(XB + (size_t)mn * D, lane, xn);
;                 const float ry = row_rstd(y);
; #pragma unroll
;                 for (int j = 0; j < 4; ++j) xv[j] += y[j] * ry * gp[j];
;                 store_row_bf16(XB + (size_t)m * D, lane, xv);
;                 const float rx = row_rstd(xv);
;                 if (lane == 0) RS2[m] = rx;
; #pragma unroll
;                 for (int j = 0; j < 4; ++j) { y[j] = yn[j]; xv[j] = xn[j]; }
;             }
.LBB0_785:
	s_mov_b32 s72, s68
	s_add_i32 s68, s68, s28
	s_cmpk_gt_i32 s68, 0x7fff
	s_cselect_b64 s[22:23], -1, 0
	s_cmp_lt_i32 s68, 0x8000
	s_cselect_b32 s2, s68, s72
	s_ashr_i32 s3, s2, 31
	s_lshl_b64 s[2:3], s[2:3], 11
	v_lshl_add_u64 v[168:169], v[162:163], 0, s[2:3]
	global_load_dwordx2 v[182:183], v[168:169], off nt
	global_load_dwordx2 v[180:181], v[168:169], off offset:512 nt
	global_load_dwordx2 v[178:179], v[168:169], off offset:1024 nt
	global_load_dwordx2 v[176:177], v[168:169], off offset:1536 nt
	v_lshl_add_u64 v[168:169], v[164:165], 0, s[2:3]
	global_load_dwordx2 v[174:175], v[168:169], off
	global_load_dwordx2 v[172:173], v[168:169], off offset:512
	global_load_dwordx2 v[170:171], v[168:169], off offset:1024
	s_nop 0
	global_load_dwordx2 v[168:169], v[168:169], off offset:1536
	v_mul_f32_e32 v0, v213, v213
	v_mul_f32_e32 v217, v215, v215
	v_fmac_f32_e32 v0, v212, v212
	v_fmac_f32_e32 v217, v214, v214
	v_add_f32_e32 v0, v0, v217
	v_mul_f32_e32 v217, v209, v209
	v_mul_f32_e32 v218, v211, v211
	v_fmac_f32_e32 v217, v208, v208
	v_fmac_f32_e32 v218, v210, v210
	v_add_f32_e32 v217, v217, v218
	v_add_f32_e32 v0, v0, v217
	v_mul_f32_e32 v217, v205, v205
	v_mul_f32_e32 v218, v207, v207
	v_fmac_f32_e32 v217, v204, v204
	v_fmac_f32_e32 v218, v206, v206
	v_add_f32_e32 v217, v217, v218
	v_add_f32_e32 v0, v0, v217
	v_mul_f32_e32 v217, v201, v201
	v_mul_f32_e32 v218, v203, v203
	v_fmac_f32_e32 v217, v200, v200
	v_fmac_f32_e32 v218, v202, v202
	v_add_f32_e32 v217, v217, v218
	v_add_f32_e32 v0, v0, v217
	s_ashr_i32 s73, s72, 31
	s_lshl_b64 s[2:3], s[72:73], 11
	v_add_f32_dpp v0, v0, v0 quad_perm:[1,0,3,2] row_mask:0xf bank_mask:0xf bound_ctrl:1
	s_nop 1
	v_add_f32_dpp v0, v0, v0 quad_perm:[2,3,0,1] row_mask:0xf bank_mask:0xf bound_ctrl:1
	s_nop 1
	v_add_f32_dpp v0, v0, v0 row_ror:4 row_mask:0xf bank_mask:0xf bound_ctrl:1
	s_nop 1
	v_add_f32_dpp v0, v0, v0 row_ror:8 row_mask:0xf bank_mask:0xf bound_ctrl:1
	v_mov_b32_e32 v217, v0
	s_nop 1
	v_permlane16_swap_b32_e32 v0, v217
	v_add_f32_e32 v0, v0, v217
	v_mov_b32_e32 v217, v0
	s_nop 1
	v_permlane32_swap_b32_e32 v0, v217
	v_add_f32_e32 v0, v0, v217
	v_fmamk_f32 v0, v0, 0x3a800000, v249
	v_rsq_f32_e32 v0, v0
	s_nop 0
	v_pk_mul_f32 v[212:213], v[0:1], v[212:213] op_sel_hi:[0,1]
	v_pk_mul_f32 v[214:215], v[0:1], v[214:215] op_sel_hi:[0,1]
	v_pk_fma_f32 v[198:199], v[214:215], v[4:5], v[198:199]
	v_pk_fma_f32 v[194:195], v[212:213], v[2:3], v[194:195]
	v_pk_mul_f32 v[200:201], v[0:1], v[200:201] op_sel_hi:[0,1]
	v_pk_mul_f32 v[208:209], v[0:1], v[208:209] op_sel_hi:[0,1]
	v_pk_mul_f32 v[210:211], v[0:1], v[210:211] op_sel_hi:[0,1]
	v_pk_mul_f32 v[204:205], v[0:1], v[204:205] op_sel_hi:[0,1]
	v_pk_mul_f32 v[206:207], v[0:1], v[206:207] op_sel_hi:[0,1]
	v_pk_mul_f32 v[202:203], v[0:1], v[202:203] op_sel_hi:[0,1]
	v_pk_fma_f32 v[184:185], v[200:201], v[14:15], v[184:185]
	v_mul_f32_e32 v0, v195, v195
	v_mul_f32_e32 v200, v199, v199
	v_pk_fma_f32 v[196:197], v[210:211], v[8:9], v[196:197]
	v_pk_fma_f32 v[190:191], v[208:209], v[6:7], v[190:191]
	v_fmac_f32_e32 v0, v194, v194
	v_fmac_f32_e32 v200, v198, v198
	v_add_f32_e32 v0, v0, v200
	v_mul_f32_e32 v200, v191, v191
	v_mul_f32_e32 v201, v197, v197
	v_fmac_f32_e32 v200, v190, v190
	v_fmac_f32_e32 v201, v196, v196
	v_pk_fma_f32 v[192:193], v[206:207], v[12:13], v[192:193]
	v_pk_fma_f32 v[186:187], v[204:205], v[10:11], v[186:187]
	v_add_f32_e32 v200, v200, v201
	v_add_f32_e32 v0, v0, v200
	v_mul_f32_e32 v200, v187, v187
	v_mul_f32_e32 v201, v193, v193
	v_fmac_f32_e32 v200, v186, v186
	v_fmac_f32_e32 v201, v192, v192
	v_pk_fma_f32 v[188:189], v[202:203], v[16:17], v[188:189]
	v_add_f32_e32 v200, v200, v201
	v_add_f32_e32 v0, v200, v0
	v_mul_f32_e32 v200, v185, v185
	v_mul_f32_e32 v201, v189, v189
	v_fmac_f32_e32 v200, v184, v184
	v_fmac_f32_e32 v201, v188, v188
	v_add_f32_e32 v200, v200, v201
	v_add_f32_e32 v0, v200, v0
	v_cvt_pk_bf16_f32 v202, v194, v195
	v_cvt_pk_bf16_f32 v203, v198, v199
	v_add_f32_dpp v0, v0, v0 quad_perm:[1,0,3,2] row_mask:0xf bank_mask:0xf bound_ctrl:1
	s_nop 1
	v_add_f32_dpp v0, v0, v0 quad_perm:[2,3,0,1] row_mask:0xf bank_mask:0xf bound_ctrl:1
	s_nop 1
	v_add_f32_dpp v0, v0, v0 row_ror:4 row_mask:0xf bank_mask:0xf bound_ctrl:1
	s_nop 1
	v_add_f32_dpp v0, v0, v0 row_ror:8 row_mask:0xf bank_mask:0xf bound_ctrl:1
	v_mov_b32_e32 v200, v0
	s_nop 1
	v_permlane16_swap_b32_e32 v0, v200
	v_add_f32_e32 v0, v0, v200
	v_mov_b32_e32 v200, v0
	s_nop 1
	v_permlane32_swap_b32_e32 v0, v200
	v_add_f32_e32 v0, v0, v200
	v_fmamk_f32 v0, v0, 0x3a800000, v249
	v_rsq_f32_e32 v0, v0
	v_lshl_add_u64 v[200:201], v[164:165], 0, s[2:3]
	global_store_dwordx2 v[200:201], v[202:203], off sc1
	v_cvt_pk_bf16_f32 v202, v190, v191
	v_cvt_pk_bf16_f32 v203, v196, v197
	global_store_dwordx2 v[200:201], v[202:203], off offset:512 sc1
	v_cvt_pk_bf16_f32 v202, v186, v187
	v_cvt_pk_bf16_f32 v203, v192, v193
	global_store_dwordx2 v[200:201], v[202:203], off offset:1024 sc1
	v_cvt_pk_bf16_f32 v202, v184, v185
	v_cvt_pk_bf16_f32 v203, v188, v189
	global_store_dwordx2 v[200:201], v[202:203], off offset:1536 sc1
	s_and_saveexec_b64 s[74:75], s[20:21]
	s_cbranch_execz .LBB0_787
	s_lshl_b64 s[2:3], s[72:73], 2
	s_add_u32 s2, s0, s2
	s_addc_u32 s3, s1, s3
	global_store_dword v1, v0, s[2:3]
